# P2 unit order: four rotations (by blockIdx&3) so at most a quarter of the workgroups stream the f32 caches at a time
# baseline (speedup 1.0000x reference)
.LBB0_450:
	v_readlane_b32 s2, v255, 15
	v_readlane_b32 s3, v255, 16
	s_andn2_b64 vcc, exec, s[2:3]
	s_cbranch_vccnz .LBB0_449
	v_readlane_b32 s3, v255, 14
	s_nop 3
	s_and_b32 s3, s3, 3
	s_lshl_b32 s3, s3, 3
	s_mov_b32 s2, 0x7839e44e
	s_lshr_b32 s2, s2, s3
	s_lshl_b32 s3, s56, 1
	s_lshr_b32 s2, s2, s3
	s_and_b32 s2, s2, 3
	s_cmp_lg_u32 s2, 0
	s_cselect_b64 s[84:85], -1, 0
	s_cmp_lg_u32 s2, 1
	s_cselect_b64 s[86:87], -1, 0
	s_cmp_eq_u32 s2, 2
	s_cselect_b64 s[88:89], -1, 0
	s_cmp_lg_u32 s2, 2
	s_cselect_b64 s[90:91], -1, 0
	s_and_b64 s[2:3], s[88:89], exec
	s_movk_i32 s2, 0x1000
	s_cselect_b32 s4, s2, 0x200
	s_or_b32 s60, s4, 32
	s_and_b64 s[2:3], s[88:89], exec
	s_cselect_b32 s2, 32, 16
	v_writelane_b32 v255, s2, 46
	s_cselect_b32 s2, 12, 9
	v_writelane_b32 v255, s2, 47
	s_cselect_b32 s2, 40, 24
	v_writelane_b32 v255, s2, 48
	s_mov_b32 s2, 0x2ce00000
	v_readlane_b32 s8, v255, 30
	v_readlane_b32 s10, v255, 32
	v_readlane_b32 s11, v255, 33
	s_cselect_b32 s2, s2, 0x2cd00000
	s_mov_b64 s[6:7], s[10:11]
	s_add_u32 s2, s6, s2
	v_readlane_b32 s9, v255, 31
	v_writelane_b32 v255, s2, 49
	s_addc_u32 s2, s7, 0
	v_writelane_b32 v255, s2, 50
	s_and_b64 s[2:3], s[88:89], exec
	s_mov_b32 s2, 0x2d100000
	s_cselect_b32 s2, s2, 0x2cf00000
	s_add_u32 s2, s6, s2
	v_writelane_b32 v255, s2, 51
	s_addc_u32 s2, s7, 0
	v_writelane_b32 v255, s2, 52
	s_and_b64 s[2:3], s[88:89], exec
	s_mov_b32 s2, 0x2d200000
	s_cselect_b32 s2, s2, 0x2d000000
	s_add_u32 s2, s6, s2
	v_writelane_b32 v255, s2, 53
	s_addc_u32 s2, s7, 0
	v_writelane_b32 v255, s2, 54
	s_lshr_b32 s61, s4, 5
	v_readlane_b32 s2, v255, 6
	v_readlane_b32 s3, v255, 7
	s_cmp_lt_u32 s2, s61
	s_cselect_b64 s[2:3], -1, 0
	v_writelane_b32 v255, s2, 55
	s_nop 1
	v_writelane_b32 v255, s3, 56
	s_and_b64 s[2:3], s[88:89], exec
	s_cselect_b32 s2, 0x400, 0
	s_add_u32 s2, s35, s2
	s_addc_u32 s3, s34, 0
	v_writelane_b32 v255, s2, 57
	s_nop 1
	v_writelane_b32 v255, s3, 58
	s_nop 0
	v_readlane_b32 s62, v255, 14
	s_branch .LBB0_453
